# baseline (speedup 1.0000x reference)
; DI unsigned pack2(float a, float b) { v2f f = {a, b}; return __builtin_bit_cast(unsigned, __builtin_convertvector(f, v2bf)); }
; DI float silu_f(float v) { return v / (1.f + fexp(-v)); }
; DI int ltid() { int x = threadIdx.x; asm volatile("" : "+v"(x)); return x; }
;   DI u32x2 pack(int, int, float a, float b, float c, float d, float&) const { u32x2 v; v.x = pack2(a, b); v.y = pack2(c, d); return v; }
; template <class ARow, class Epi>
; DI void gemm_tile(const ARow& arow, long a_kstride, const u16* __restrict__ Bt, long ldb, int K, int m0, int n0,
;                   const Epi& epi, char* smem) {
;     ...
;   if (epi.packed(nh)) {
; #pragma unroll
;     for (int mi = 0; mi < 4; ++mi) {
;       const int m = m0 + wm * 64 + mi * 16 + fr;
;       float ss = 0.f;
;       u32x2 pk[4];
; #pragma unroll
;       for (int ni = 0; ni < 4; ++ni) pk[ni] = epi.pack(m, nh + ni * 16 + fq * 4, acc[ni][mi][0], acc[ni][mi][1], acc[ni][mi][2], acc[ni][mi][3], ss);
;       epi.finish16(m, nh, ss);
;   DI u32x2 pack(int m, int n, float a, float b, float c, float d, float& ss) const {
;     if (n < q_end) { a *= qscale; b *= qscale; c *= qscale; d *= qscale; }
;     else if (n >= z_start) { a = silu_f(a); b = silu_f(b); c = silu_f(c); d = silu_f(d); }
;     ss += a * a + b * b + c * c + d * d;
;     u32x2 v; v.x = pack2(a, b); v.y = pack2(c, d);
;     return v;
;   }
;   DI void finish16(int m, int nh, float ss) const {
;     if (nh >= kn_lo && nh < kn_hi) {
;       ss += __shfl_xor(ss, 16); ss += __shfl_xor(ss, 32);
; #pragma unroll
;       for (int o = 8; o > 0; o >>= 1) ss = fmaxf(ss, __shfl_xor(ss, o));
;       if ((ltid() & 63) == 0) atomicMax(kmax2 + (m >> 13) * 64 + (nh >> 6), __float_as_uint(ss));
;     }
.Lfe_A_not_z:
	s_cmpk_ge_u32 s99, 0x400
	s_cbranch_scc0 .Lfe_A_not_k
	s_cmpk_lt_u32 s99, 0xa00
	s_cbranch_scc0 .Lfe_A_not_k
	s_load_dwordx2 s[100:101], s[56:57], 0x130
	v_and_b32_e32 v152, 1, v84
	v_mul_u32_u24_e32 v152, 12, v152
	v_lshl_add_u32 v152, v84, 2, v152
	v_add_u32_e32 v152, v152, v66
	v_mul_u32_u24_e32 v153, 0xe00, v74
	v_add_u32_e32 v152, v152, v153
	v_lshlrev_b32_e32 v152, 1, v152
	v_add_u32_e32 v153, 0x1c000, v152
	v_add_u32_e32 v154, 0x38000, v152
	v_add_u32_e32 v155, 0x54000, v152
	s_load_dwordx2 s[98:99], s[56:57], 0x100
	v_lshrrev_b32_e32 v174, 6, v66
	v_lshrrev_b32_e32 v175, 13, v74
	v_lshl_add_u32 v174, v175, 6, v174
	v_lshlrev_b32_e32 v174, 2, v174
	s_waitcnt lgkmcnt(0)
	global_load_dword v177, v174, s[98:99] sc1
	s_nop 3
	v_pk_mul_f32 v[156:157], v[60:61], v[60:61]
	v_pk_mul_f32 v[158:159], v[62:63], v[62:63]
	v_pk_mul_f32 v[160:161], v[56:57], v[56:57]
	v_pk_mul_f32 v[162:163], v[58:59], v[58:59]
	v_pk_mul_f32 v[164:165], v[52:53], v[52:53]
	v_pk_mul_f32 v[166:167], v[54:55], v[54:55]
	v_pk_mul_f32 v[168:169], v[48:49], v[48:49]
	v_pk_mul_f32 v[170:171], v[50:51], v[50:51]
	v_add_f32_e32 v172, v157, v156
	v_add_f32_e32 v172, v158, v172
	v_add_f32_e32 v172, v159, v172
	v_add_f32_e32 v173, v161, v160
	v_add_f32_e32 v173, v162, v173
	v_add_f32_e32 v173, v163, v173
	v_add_f32_e32 v172, v172, v173
	v_add_f32_e32 v173, v165, v164
	v_add_f32_e32 v173, v166, v173
	v_add_f32_e32 v173, v167, v173
	v_add_f32_e32 v172, v172, v173
	v_add_f32_e32 v173, v169, v168
	v_add_f32_e32 v173, v170, v173
	v_add_f32_e32 v173, v171, v173
	v_add_f32_e32 v172, v172, v173
	v_mov_b32_e32 v173, v172
	s_nop 1
	v_permlane16_swap_b32_e32 v173, v172
	v_add_f32_e32 v172, v172, v173
	v_mov_b32_e32 v173, v172
	s_nop 1
	v_permlane32_swap_b32_e32 v173, v172
	v_add_f32_e32 v172, v172, v173
	s_nop 1
	v_max_f32_dpp v172, v172, v172 row_ror:8 row_mask:0xf bank_mask:0xf
	s_nop 1
	v_max_f32_dpp v173, v172, v172 row_shl:4 row_mask:0xf bank_mask:0x5
	v_max_f32_dpp v173, v172, v172 row_shr:4 row_mask:0xf bank_mask:0xa
	s_nop 1
	v_max_f32_dpp v172, v173, v173 quad_perm:[2,3,0,1] row_mask:0xf bank_mask:0xf
	s_nop 1
	v_max_f32_dpp v172, v172, v172 quad_perm:[1,0,3,2] row_mask:0xf bank_mask:0xf
	v_mov_b32_e32 v176, v172
	v_pk_mul_f32 v[156:157], v[44:45], v[44:45]
	v_pk_mul_f32 v[158:159], v[46:47], v[46:47]
	v_pk_mul_f32 v[160:161], v[40:41], v[40:41]
	v_pk_mul_f32 v[162:163], v[42:43], v[42:43]
	v_pk_mul_f32 v[164:165], v[36:37], v[36:37]
	v_pk_mul_f32 v[166:167], v[38:39], v[38:39]
	v_pk_mul_f32 v[168:169], v[32:33], v[32:33]
	v_pk_mul_f32 v[170:171], v[34:35], v[34:35]
	v_add_f32_e32 v172, v157, v156
	v_add_f32_e32 v172, v158, v172
	v_add_f32_e32 v172, v159, v172
	v_add_f32_e32 v173, v161, v160
	v_add_f32_e32 v173, v162, v173
	v_add_f32_e32 v173, v163, v173
	v_add_f32_e32 v172, v172, v173
	v_add_f32_e32 v173, v165, v164
	v_add_f32_e32 v173, v166, v173
	v_add_f32_e32 v173, v167, v173
	v_add_f32_e32 v172, v172, v173
	v_add_f32_e32 v173, v169, v168
	v_add_f32_e32 v173, v170, v173
	v_add_f32_e32 v173, v171, v173
	v_add_f32_e32 v172, v172, v173
	v_mov_b32_e32 v173, v172
	s_nop 1
	v_permlane16_swap_b32_e32 v173, v172
	v_add_f32_e32 v172, v172, v173
	v_mov_b32_e32 v173, v172
	s_nop 1
	v_permlane32_swap_b32_e32 v173, v172
	v_add_f32_e32 v172, v172, v173
	s_nop 1
	v_max_f32_dpp v172, v172, v172 row_ror:8 row_mask:0xf bank_mask:0xf
	s_nop 1
	v_max_f32_dpp v173, v172, v172 row_shl:4 row_mask:0xf bank_mask:0x5
	v_max_f32_dpp v173, v172, v172 row_shr:4 row_mask:0xf bank_mask:0xa
	s_nop 1
	v_max_f32_dpp v172, v173, v173 quad_perm:[2,3,0,1] row_mask:0xf bank_mask:0xf
	s_nop 1
	v_max_f32_dpp v172, v172, v172 quad_perm:[1,0,3,2] row_mask:0xf bank_mask:0xf
	v_max_f32_e32 v176, v176, v172
	v_pk_mul_f32 v[156:157], v[28:29], v[28:29]
	v_pk_mul_f32 v[158:159], v[30:31], v[30:31]
	v_pk_mul_f32 v[160:161], v[24:25], v[24:25]
	v_pk_mul_f32 v[162:163], v[26:27], v[26:27]
	v_pk_mul_f32 v[164:165], v[20:21], v[20:21]
	v_pk_mul_f32 v[166:167], v[22:23], v[22:23]
	v_pk_mul_f32 v[168:169], v[16:17], v[16:17]
	v_pk_mul_f32 v[170:171], v[18:19], v[18:19]
	v_add_f32_e32 v172, v157, v156
	v_add_f32_e32 v172, v158, v172
	v_add_f32_e32 v172, v159, v172
	v_add_f32_e32 v173, v161, v160
	v_add_f32_e32 v173, v162, v173
	v_add_f32_e32 v173, v163, v173
	v_add_f32_e32 v172, v172, v173
	v_add_f32_e32 v173, v165, v164
	v_add_f32_e32 v173, v166, v173
	v_add_f32_e32 v173, v167, v173
	v_add_f32_e32 v172, v172, v173
	v_add_f32_e32 v173, v169, v168
	v_add_f32_e32 v173, v170, v173
	v_add_f32_e32 v173, v171, v173
	v_add_f32_e32 v172, v172, v173
	v_mov_b32_e32 v173, v172
	s_nop 1
	v_permlane16_swap_b32_e32 v173, v172
	v_add_f32_e32 v172, v172, v173
	v_mov_b32_e32 v173, v172
	s_nop 1
	v_permlane32_swap_b32_e32 v173, v172
	v_add_f32_e32 v172, v172, v173
	s_nop 1
	v_max_f32_dpp v172, v172, v172 row_ror:8 row_mask:0xf bank_mask:0xf
	s_nop 1
	v_max_f32_dpp v173, v172, v172 row_shl:4 row_mask:0xf bank_mask:0x5
	v_max_f32_dpp v173, v172, v172 row_shr:4 row_mask:0xf bank_mask:0xa
	s_nop 1
	v_max_f32_dpp v172, v173, v173 quad_perm:[2,3,0,1] row_mask:0xf bank_mask:0xf
	s_nop 1
	v_max_f32_dpp v172, v172, v172 quad_perm:[1,0,3,2] row_mask:0xf bank_mask:0xf
	v_max_f32_e32 v176, v176, v172
	v_pk_mul_f32 v[156:157], v[12:13], v[12:13]
	v_pk_mul_f32 v[158:159], v[14:15], v[14:15]
	v_pk_mul_f32 v[160:161], v[8:9], v[8:9]
	v_pk_mul_f32 v[162:163], v[10:11], v[10:11]
	v_pk_mul_f32 v[164:165], v[4:5], v[4:5]
	v_pk_mul_f32 v[166:167], v[6:7], v[6:7]
	v_pk_mul_f32 v[168:169], v[0:1], v[0:1]
	v_pk_mul_f32 v[170:171], v[2:3], v[2:3]
	v_add_f32_e32 v172, v157, v156
	v_add_f32_e32 v172, v158, v172
	v_add_f32_e32 v172, v159, v172
	v_add_f32_e32 v173, v161, v160
	v_add_f32_e32 v173, v162, v173
	v_add_f32_e32 v173, v163, v173
	v_add_f32_e32 v172, v172, v173
	v_add_f32_e32 v173, v165, v164
	v_add_f32_e32 v173, v166, v173
	v_add_f32_e32 v173, v167, v173
	v_add_f32_e32 v172, v172, v173
	v_add_f32_e32 v173, v169, v168
	v_add_f32_e32 v173, v170, v173
	v_add_f32_e32 v173, v171, v173
	v_add_f32_e32 v172, v172, v173
	v_mov_b32_e32 v173, v172
	s_nop 1
	v_permlane16_swap_b32_e32 v173, v172
	v_add_f32_e32 v172, v172, v173
	v_mov_b32_e32 v173, v172
	s_nop 1
	v_permlane32_swap_b32_e32 v173, v172
	v_add_f32_e32 v172, v172, v173
	s_nop 1
	v_max_f32_dpp v172, v172, v172 row_ror:8 row_mask:0xf bank_mask:0xf
	s_nop 1
	v_max_f32_dpp v173, v172, v172 row_shl:4 row_mask:0xf bank_mask:0x5
	v_max_f32_dpp v173, v172, v172 row_shr:4 row_mask:0xf bank_mask:0xa
	s_nop 1
	v_max_f32_dpp v172, v173, v173 quad_perm:[2,3,0,1] row_mask:0xf bank_mask:0xf
	s_nop 1
	v_max_f32_dpp v172, v172, v172 quad_perm:[1,0,3,2] row_mask:0xf bank_mask:0xf
	v_max_f32_e32 v176, v176, v172
	v_and_b32_e32 v175, 63, v222
	v_cmp_eq_u32_e32 vcc, 0, v175
	s_waitcnt lgkmcnt(0)
; DI int ltid() { int x = threadIdx.x; asm volatile("" : "+v"(x)); return x; }
; template <class ARow, class Epi>
; DI void gemm_tile(const ARow& arow, long a_kstride, const u16* __restrict__ Bt, long ldb, int K, int m0, int n0,
;                   const Epi& epi, char* smem) {
;     ...
;       u16* rp = epi.rowp(m) + nh;
; #pragma unroll
;       for (int pp = 0; pp < 2; ++pp) {
;         u32x2 a = pk[2 * pp], b = pk[2 * pp + 1];
;         const u32x2 rx = __builtin_amdgcn_permlane16_swap(a.x, b.x, false, false);
;         const u32x2 ry = __builtin_amdgcn_permlane16_swap(a.y, b.y, false, false);
;         const int nst = (fq & 1) ? ((2 * pp + 1) * 16 + (fq - 1) * 4) : ((2 * pp) * 16 + fq * 4);
;         *(u32x4*)(rp + nst) = (u32x4){rx[0], ry[0], rx[1], ry[1]};
;       }
;   DI void finish16(int m, int nh, float ss) const {
;     if (nh >= kn_lo && nh < kn_hi) {
;       ss += __shfl_xor(ss, 16); ss += __shfl_xor(ss, 32);
; #pragma unroll
;       for (int o = 8; o > 0; o >>= 1) ss = fmaxf(ss, __shfl_xor(ss, o));
;       if ((ltid() & 63) == 0) atomicMax(kmax2 + (m >> 13) * 64 + (nh >> 6), __float_as_uint(ss));
;     }
	s_and_b64 exec, exec, vcc
	s_waitcnt vmcnt(0)
	v_cmp_gt_u32_e32 vcc, v176, v177
	s_and_b64 exec, exec, vcc
	global_atomic_umax v174, v176, s[98:99]
	s_mov_b64 exec, -1
	s_nop 3
	v_cvt_pk_bf16_f32 v120, v60, v61
	v_cvt_pk_bf16_f32 v121, v62, v63
	v_cvt_pk_bf16_f32 v122, v56, v57
	v_cvt_pk_bf16_f32 v123, v58, v59
	v_cvt_pk_bf16_f32 v124, v52, v53
	v_cvt_pk_bf16_f32 v125, v54, v55
	v_cvt_pk_bf16_f32 v126, v48, v49
	v_cvt_pk_bf16_f32 v127, v50, v51
	s_nop 1
	v_permlane16_swap_b32_e32 v120, v122
	v_permlane16_swap_b32_e32 v121, v123
	v_permlane16_swap_b32_e32 v124, v126
	v_permlane16_swap_b32_e32 v125, v127
	s_waitcnt lgkmcnt(0)
	global_store_dwordx4 v152, v[120:123], s[100:101]
	global_store_dwordx4 v152, v[124:127], s[100:101] offset:64
	v_cvt_pk_bf16_f32 v128, v44, v45
	v_cvt_pk_bf16_f32 v129, v46, v47
	v_cvt_pk_bf16_f32 v130, v40, v41
	v_cvt_pk_bf16_f32 v131, v42, v43
	v_cvt_pk_bf16_f32 v132, v36, v37
	v_cvt_pk_bf16_f32 v133, v38, v39
	v_cvt_pk_bf16_f32 v134, v32, v33
	v_cvt_pk_bf16_f32 v135, v34, v35
	s_nop 1
	v_permlane16_swap_b32_e32 v128, v130
	v_permlane16_swap_b32_e32 v129, v131
	v_permlane16_swap_b32_e32 v132, v134
	v_permlane16_swap_b32_e32 v133, v135
	global_store_dwordx4 v153, v[128:131], s[100:101]
	global_store_dwordx4 v153, v[132:135], s[100:101] offset:64
	v_cvt_pk_bf16_f32 v136, v28, v29
	v_cvt_pk_bf16_f32 v137, v30, v31
	v_cvt_pk_bf16_f32 v138, v24, v25
	v_cvt_pk_bf16_f32 v139, v26, v27
	v_cvt_pk_bf16_f32 v140, v20, v21
	v_cvt_pk_bf16_f32 v141, v22, v23
	v_cvt_pk_bf16_f32 v142, v16, v17
	v_cvt_pk_bf16_f32 v143, v18, v19
	s_nop 1
	v_permlane16_swap_b32_e32 v136, v138
	v_permlane16_swap_b32_e32 v137, v139
	v_permlane16_swap_b32_e32 v140, v142
	v_permlane16_swap_b32_e32 v141, v143
	global_store_dwordx4 v154, v[136:139], s[100:101]
	global_store_dwordx4 v154, v[140:143], s[100:101] offset:64
	v_cvt_pk_bf16_f32 v144, v12, v13
	v_cvt_pk_bf16_f32 v145, v14, v15
	v_cvt_pk_bf16_f32 v146, v8, v9
	v_cvt_pk_bf16_f32 v147, v10, v11
	v_cvt_pk_bf16_f32 v148, v4, v5
	v_cvt_pk_bf16_f32 v149, v6, v7
	v_cvt_pk_bf16_f32 v150, v0, v1
	v_cvt_pk_bf16_f32 v151, v2, v3
	s_nop 1
	v_permlane16_swap_b32_e32 v144, v146
	v_permlane16_swap_b32_e32 v145, v147
	v_permlane16_swap_b32_e32 v148, v150
	v_permlane16_swap_b32_e32 v149, v151
	global_store_dwordx4 v155, v[144:147], s[100:101]
	global_store_dwordx4 v155, v[148:151], s[100:101] offset:64
	s_branch .Lfe_join_A

; DI unsigned pack2(float a, float b) { v2f f = {a, b}; return __builtin_bit_cast(unsigned, __builtin_convertvector(f, v2bf)); }
; DI float silu_f(float v) { return v / (1.f + fexp(-v)); }
; DI int ltid() { int x = threadIdx.x; asm volatile("" : "+v"(x)); return x; }
;   DI u32x2 pack(int, int, float a, float b, float c, float d, float&) const { u32x2 v; v.x = pack2(a, b); v.y = pack2(c, d); return v; }
; template <class ARow, class Epi>
; DI void gemm_tile(const ARow& arow, long a_kstride, const u16* __restrict__ Bt, long ldb, int K, int m0, int n0,
;                   const Epi& epi, char* smem) {
;     ...
;     for (int mi = 0; mi < 4; ++mi) {
;       const int m = m0 + wm * 64 + mi * 16 + fr;
;       float ss = 0.f;
;       u32x2 pk[4];
; #pragma unroll
;       for (int ni = 0; ni < 4; ++ni) pk[ni] = epi.pack(m, nh + ni * 16 + fq * 4, acc[ni][mi][0], acc[ni][mi][1], acc[ni][mi][2], acc[ni][mi][3], ss);
;       epi.finish16(m, nh, ss);
;   DI u32x2 pack(int m, int n, float a, float b, float c, float d, float& ss) const {
;     if (n < q_end) { a *= qscale; b *= qscale; c *= qscale; d *= qscale; }
;     else if (n >= z_start) { a = silu_f(a); b = silu_f(b); c = silu_f(c); d = silu_f(d); }
;     ss += a * a + b * b + c * c + d * d;
;     u32x2 v; v.x = pack2(a, b); v.y = pack2(c, d);
;     return v;
;   }
;   DI void finish16(int m, int nh, float ss) const {
;     if (nh >= kn_lo && nh < kn_hi) {
;       ss += __shfl_xor(ss, 16); ss += __shfl_xor(ss, 32);
; #pragma unroll
;       for (int o = 8; o > 0; o >>= 1) ss = fmaxf(ss, __shfl_xor(ss, o));
;       if ((ltid() & 63) == 0) atomicMax(kmax2 + (m >> 13) * 64 + (nh >> 6), __float_as_uint(ss));
.Lfe_B_not_z:
	s_cmpk_ge_u32 s99, 0x400
	s_cbranch_scc0 .Lfe_B_not_k
	s_cmpk_lt_u32 s99, 0x800
	s_cbranch_scc0 .Lfe_B_not_k
	s_load_dwordx2 s[100:101], s[56:57], 0x130
	v_and_b32_e32 v152, 1, v84
	v_mul_u32_u24_e32 v152, 12, v152
	v_lshl_add_u32 v152, v84, 2, v152
	v_add_u32_e32 v152, v152, v68
	v_lshl_add_u32 v152, v66, 12, v152
	v_lshlrev_b32_e32 v152, 1, v152
	v_add_u32_e32 v153, 0x20000, v152
	v_add_u32_e32 v154, 0x40000, v152
	v_add_u32_e32 v155, 0x60000, v152
	s_load_dwordx2 s[98:99], s[56:57], 0x100
	v_lshrrev_b32_e32 v174, 6, v68
	v_lshrrev_b32_e32 v175, 13, v66
	v_lshl_add_u32 v174, v175, 6, v174
	v_lshlrev_b32_e32 v174, 2, v174
	s_waitcnt lgkmcnt(0)
	global_load_dword v177, v174, s[98:99] offset:512 sc1
	s_nop 3
	v_pk_mul_f32 v[156:157], v[60:61], v[60:61]
	v_pk_mul_f32 v[158:159], v[62:63], v[62:63]
	v_pk_mul_f32 v[160:161], v[56:57], v[56:57]
	v_pk_mul_f32 v[162:163], v[58:59], v[58:59]
	v_pk_mul_f32 v[164:165], v[52:53], v[52:53]
	v_pk_mul_f32 v[166:167], v[54:55], v[54:55]
	v_pk_mul_f32 v[168:169], v[48:49], v[48:49]
	v_pk_mul_f32 v[170:171], v[50:51], v[50:51]
	v_add_f32_e32 v172, v157, v156
	v_add_f32_e32 v172, v158, v172
	v_add_f32_e32 v172, v159, v172
	v_add_f32_e32 v173, v161, v160
	v_add_f32_e32 v173, v162, v173
	v_add_f32_e32 v173, v163, v173
	v_add_f32_e32 v172, v172, v173
	v_add_f32_e32 v173, v165, v164
	v_add_f32_e32 v173, v166, v173
	v_add_f32_e32 v173, v167, v173
	v_add_f32_e32 v172, v172, v173
	v_add_f32_e32 v173, v169, v168
	v_add_f32_e32 v173, v170, v173
	v_add_f32_e32 v173, v171, v173
	v_add_f32_e32 v172, v172, v173
	v_mov_b32_e32 v173, v172
	s_nop 1
	v_permlane16_swap_b32_e32 v173, v172
	v_add_f32_e32 v172, v172, v173
	v_mov_b32_e32 v173, v172
	s_nop 1
	v_permlane32_swap_b32_e32 v173, v172
	v_add_f32_e32 v172, v172, v173
	s_nop 1
	v_max_f32_dpp v172, v172, v172 row_ror:8 row_mask:0xf bank_mask:0xf
	s_nop 1
	v_max_f32_dpp v173, v172, v172 row_shl:4 row_mask:0xf bank_mask:0x5
	v_max_f32_dpp v173, v172, v172 row_shr:4 row_mask:0xf bank_mask:0xa
	s_nop 1
	v_max_f32_dpp v172, v173, v173 quad_perm:[2,3,0,1] row_mask:0xf bank_mask:0xf
	s_nop 1
	v_max_f32_dpp v172, v172, v172 quad_perm:[1,0,3,2] row_mask:0xf bank_mask:0xf
	v_mov_b32_e32 v176, v172
	v_pk_mul_f32 v[156:157], v[44:45], v[44:45]
	v_pk_mul_f32 v[158:159], v[46:47], v[46:47]
	v_pk_mul_f32 v[160:161], v[40:41], v[40:41]
	v_pk_mul_f32 v[162:163], v[42:43], v[42:43]
	v_pk_mul_f32 v[164:165], v[36:37], v[36:37]
	v_pk_mul_f32 v[166:167], v[38:39], v[38:39]
	v_pk_mul_f32 v[168:169], v[32:33], v[32:33]
	v_pk_mul_f32 v[170:171], v[34:35], v[34:35]
	v_add_f32_e32 v172, v157, v156
	v_add_f32_e32 v172, v158, v172
	v_add_f32_e32 v172, v159, v172
	v_add_f32_e32 v173, v161, v160
	v_add_f32_e32 v173, v162, v173
	v_add_f32_e32 v173, v163, v173
	v_add_f32_e32 v172, v172, v173
	v_add_f32_e32 v173, v165, v164
	v_add_f32_e32 v173, v166, v173
	v_add_f32_e32 v173, v167, v173
	v_add_f32_e32 v172, v172, v173
	v_add_f32_e32 v173, v169, v168
	v_add_f32_e32 v173, v170, v173
	v_add_f32_e32 v173, v171, v173
	v_add_f32_e32 v172, v172, v173
	v_mov_b32_e32 v173, v172
	s_nop 1
	v_permlane16_swap_b32_e32 v173, v172
	v_add_f32_e32 v172, v172, v173
	v_mov_b32_e32 v173, v172
	s_nop 1
	v_permlane32_swap_b32_e32 v173, v172
	v_add_f32_e32 v172, v172, v173
	s_nop 1
	v_max_f32_dpp v172, v172, v172 row_ror:8 row_mask:0xf bank_mask:0xf
	s_nop 1
	v_max_f32_dpp v173, v172, v172 row_shl:4 row_mask:0xf bank_mask:0x5
	v_max_f32_dpp v173, v172, v172 row_shr:4 row_mask:0xf bank_mask:0xa
	s_nop 1
	v_max_f32_dpp v172, v173, v173 quad_perm:[2,3,0,1] row_mask:0xf bank_mask:0xf
	s_nop 1
	v_max_f32_dpp v172, v172, v172 quad_perm:[1,0,3,2] row_mask:0xf bank_mask:0xf
	v_max_f32_e32 v176, v176, v172
	v_pk_mul_f32 v[156:157], v[28:29], v[28:29]
	v_pk_mul_f32 v[158:159], v[30:31], v[30:31]
	v_pk_mul_f32 v[160:161], v[24:25], v[24:25]
	v_pk_mul_f32 v[162:163], v[26:27], v[26:27]
	v_pk_mul_f32 v[164:165], v[20:21], v[20:21]
	v_pk_mul_f32 v[166:167], v[22:23], v[22:23]
	v_pk_mul_f32 v[168:169], v[16:17], v[16:17]
	v_pk_mul_f32 v[170:171], v[18:19], v[18:19]
	v_add_f32_e32 v172, v157, v156
	v_add_f32_e32 v172, v158, v172
	v_add_f32_e32 v172, v159, v172
	v_add_f32_e32 v173, v161, v160
	v_add_f32_e32 v173, v162, v173
	v_add_f32_e32 v173, v163, v173
	v_add_f32_e32 v172, v172, v173
	v_add_f32_e32 v173, v165, v164
	v_add_f32_e32 v173, v166, v173
	v_add_f32_e32 v173, v167, v173
	v_add_f32_e32 v172, v172, v173
	v_add_f32_e32 v173, v169, v168
	v_add_f32_e32 v173, v170, v173
	v_add_f32_e32 v173, v171, v173
	v_add_f32_e32 v172, v172, v173
	v_mov_b32_e32 v173, v172
	s_nop 1
	v_permlane16_swap_b32_e32 v173, v172
	v_add_f32_e32 v172, v172, v173
	v_mov_b32_e32 v173, v172
	s_nop 1
	v_permlane32_swap_b32_e32 v173, v172
	v_add_f32_e32 v172, v172, v173
	s_nop 1
	v_max_f32_dpp v172, v172, v172 row_ror:8 row_mask:0xf bank_mask:0xf
	s_nop 1
	v_max_f32_dpp v173, v172, v172 row_shl:4 row_mask:0xf bank_mask:0x5
	v_max_f32_dpp v173, v172, v172 row_shr:4 row_mask:0xf bank_mask:0xa
	s_nop 1
	v_max_f32_dpp v172, v173, v173 quad_perm:[2,3,0,1] row_mask:0xf bank_mask:0xf
	s_nop 1
	v_max_f32_dpp v172, v172, v172 quad_perm:[1,0,3,2] row_mask:0xf bank_mask:0xf
	v_max_f32_e32 v176, v176, v172
	v_pk_mul_f32 v[156:157], v[12:13], v[12:13]
	v_pk_mul_f32 v[158:159], v[14:15], v[14:15]
	v_pk_mul_f32 v[160:161], v[8:9], v[8:9]
	v_pk_mul_f32 v[162:163], v[10:11], v[10:11]
	v_pk_mul_f32 v[164:165], v[4:5], v[4:5]
	v_pk_mul_f32 v[166:167], v[6:7], v[6:7]
	v_pk_mul_f32 v[168:169], v[0:1], v[0:1]
	v_pk_mul_f32 v[170:171], v[2:3], v[2:3]
	v_add_f32_e32 v172, v157, v156
	v_add_f32_e32 v172, v158, v172
	v_add_f32_e32 v172, v159, v172
	v_add_f32_e32 v173, v161, v160
	v_add_f32_e32 v173, v162, v173
	v_add_f32_e32 v173, v163, v173
	v_add_f32_e32 v172, v172, v173
	v_add_f32_e32 v173, v165, v164
	v_add_f32_e32 v173, v166, v173
	v_add_f32_e32 v173, v167, v173
	v_add_f32_e32 v172, v172, v173
	v_add_f32_e32 v173, v169, v168
	v_add_f32_e32 v173, v170, v173
	v_add_f32_e32 v173, v171, v173
	v_add_f32_e32 v172, v172, v173
	v_mov_b32_e32 v173, v172
	s_nop 1
	v_permlane16_swap_b32_e32 v173, v172
	v_add_f32_e32 v172, v172, v173
	v_mov_b32_e32 v173, v172
	s_nop 1
	v_permlane32_swap_b32_e32 v173, v172
	v_add_f32_e32 v172, v172, v173
	s_nop 1
	v_max_f32_dpp v172, v172, v172 row_ror:8 row_mask:0xf bank_mask:0xf
	s_nop 1
	v_max_f32_dpp v173, v172, v172 row_shl:4 row_mask:0xf bank_mask:0x5
	v_max_f32_dpp v173, v172, v172 row_shr:4 row_mask:0xf bank_mask:0xa
	s_nop 1
	v_max_f32_dpp v172, v173, v173 quad_perm:[2,3,0,1] row_mask:0xf bank_mask:0xf
	s_nop 1
	v_max_f32_dpp v172, v172, v172 quad_perm:[1,0,3,2] row_mask:0xf bank_mask:0xf
	v_max_f32_e32 v176, v176, v172
	v_and_b32_e32 v175, 63, v222
	v_cmp_eq_u32_e32 vcc, 0, v175
	s_waitcnt lgkmcnt(0)
; DI int ltid() { int x = threadIdx.x; asm volatile("" : "+v"(x)); return x; }
; template <class ARow, class Epi>
; DI void gemm_tile(const ARow& arow, long a_kstride, const u16* __restrict__ Bt, long ldb, int K, int m0, int n0,
;                   const Epi& epi, char* smem) {
;     ...
;       u16* rp = epi.rowp(m) + nh;
; #pragma unroll
;       for (int pp = 0; pp < 2; ++pp) {
;         u32x2 a = pk[2 * pp], b = pk[2 * pp + 1];
;         const u32x2 rx = __builtin_amdgcn_permlane16_swap(a.x, b.x, false, false);
;         const u32x2 ry = __builtin_amdgcn_permlane16_swap(a.y, b.y, false, false);
;         const int nst = (fq & 1) ? ((2 * pp + 1) * 16 + (fq - 1) * 4) : ((2 * pp) * 16 + fq * 4);
;         *(u32x4*)(rp + nst) = (u32x4){rx[0], ry[0], rx[1], ry[1]};
;       }
;   DI void finish16(int m, int nh, float ss) const {
;     ...
;       if ((ltid() & 63) == 0) atomicMax(kmax2 + (m >> 13) * 64 + (nh >> 6), __float_as_uint(ss));
	s_and_b64 exec, exec, vcc
	s_waitcnt vmcnt(0)
	v_cmp_gt_u32_e32 vcc, v176, v177
	s_and_b64 exec, exec, vcc
	global_atomic_umax v174, v176, s[98:99] offset:512
	s_mov_b64 exec, -1
	s_nop 3
	v_cvt_pk_bf16_f32 v120, v60, v61
	v_cvt_pk_bf16_f32 v121, v62, v63
	v_cvt_pk_bf16_f32 v122, v56, v57
	v_cvt_pk_bf16_f32 v123, v58, v59
	v_cvt_pk_bf16_f32 v124, v52, v53
	v_cvt_pk_bf16_f32 v125, v54, v55
	v_cvt_pk_bf16_f32 v126, v48, v49
	v_cvt_pk_bf16_f32 v127, v50, v51
	s_nop 1
	v_permlane16_swap_b32_e32 v120, v122
	v_permlane16_swap_b32_e32 v121, v123
	v_permlane16_swap_b32_e32 v124, v126
	v_permlane16_swap_b32_e32 v125, v127
	s_waitcnt lgkmcnt(0)
	global_store_dwordx4 v152, v[120:123], s[100:101]
	global_store_dwordx4 v152, v[124:127], s[100:101] offset:64
	v_cvt_pk_bf16_f32 v128, v44, v45
	v_cvt_pk_bf16_f32 v129, v46, v47
	v_cvt_pk_bf16_f32 v130, v40, v41
	v_cvt_pk_bf16_f32 v131, v42, v43
	v_cvt_pk_bf16_f32 v132, v36, v37
	v_cvt_pk_bf16_f32 v133, v38, v39
	v_cvt_pk_bf16_f32 v134, v32, v33
	v_cvt_pk_bf16_f32 v135, v34, v35
	s_nop 1
	v_permlane16_swap_b32_e32 v128, v130
	v_permlane16_swap_b32_e32 v129, v131
	v_permlane16_swap_b32_e32 v132, v134
	v_permlane16_swap_b32_e32 v133, v135
	global_store_dwordx4 v153, v[128:131], s[100:101]
	global_store_dwordx4 v153, v[132:135], s[100:101] offset:64
	v_cvt_pk_bf16_f32 v136, v28, v29
	v_cvt_pk_bf16_f32 v137, v30, v31
	v_cvt_pk_bf16_f32 v138, v24, v25
	v_cvt_pk_bf16_f32 v139, v26, v27
	v_cvt_pk_bf16_f32 v140, v20, v21
	v_cvt_pk_bf16_f32 v141, v22, v23
	v_cvt_pk_bf16_f32 v142, v16, v17
	v_cvt_pk_bf16_f32 v143, v18, v19
	s_nop 1
	v_permlane16_swap_b32_e32 v136, v138
	v_permlane16_swap_b32_e32 v137, v139
	v_permlane16_swap_b32_e32 v140, v142
	v_permlane16_swap_b32_e32 v141, v143
	global_store_dwordx4 v154, v[136:139], s[100:101]
	global_store_dwordx4 v154, v[140:143], s[100:101] offset:64
	v_cvt_pk_bf16_f32 v144, v12, v13
	v_cvt_pk_bf16_f32 v145, v14, v15
	v_cvt_pk_bf16_f32 v146, v8, v9
	v_cvt_pk_bf16_f32 v147, v10, v11
	v_cvt_pk_bf16_f32 v148, v4, v5
	v_cvt_pk_bf16_f32 v149, v6, v7
	v_cvt_pk_bf16_f32 v150, v0, v1
	v_cvt_pk_bf16_f32 v151, v2, v3
	s_nop 1
	v_permlane16_swap_b32_e32 v144, v146
	v_permlane16_swap_b32_e32 v145, v147
	v_permlane16_swap_b32_e32 v148, v150
	v_permlane16_swap_b32_e32 v149, v151
	global_store_dwordx4 v155, v[144:147], s[100:101]
	global_store_dwordx4 v155, v[148:151], s[100:101] offset:64
	s_branch .Lfe_join_B
